# LRU output section: 16 row pairs read from LDS in one batch after the scan barrier
# speedup vs baseline: 1.0024x; 1.0014x over previous
.LBB0_1093:
	s_waitcnt vmcnt(15)
	v_lshlrev_b32_e32 v163, 16, v163
	v_mul_f32_e32 v165, 0x3d372713, v163
	v_mul_f32_e32 v165, v165, v163
	v_fma_f32 v165, v165, v163, v163
	v_mul_f32_e32 v165, 0x3fcc422a, v165
	v_mul_f32_e32 v165, 0xbfb8aa3b, v165
	v_exp_f32_e32 v165, v165
	s_add_i32 s11, s11, 1
	s_cmp_lg_u32 s11, 16
	v_add_f32_e32 v165, 1.0, v165
	v_rcp_f32_e32 v165, v165
	s_waitcnt lgkmcnt(0)
	v_fma_f32 v111, v110, v182, v166
	v_mul_f32_e32 v163, v165, v163
	v_mul_f32_e32 v111, v163, v111
	v_cvt_pk_bf16_f32 v111, v111, v113
	global_store_short v[66:67], v111, off offset:2048
	s_waitcnt vmcnt(15)
	v_lshlrev_b32_e32 v111, 16, v162
	v_mul_f32_e32 v162, 0x3d372713, v111
	v_mul_f32_e32 v162, v162, v111
	v_fma_f32 v162, v162, v111, v111
	v_mul_f32_e32 v162, 0x3fcc422a, v162
	v_mul_f32_e32 v162, 0xbfb8aa3b, v162
	v_exp_f32_e32 v162, v162
	s_nop 0
	v_add_f32_e32 v162, 1.0, v162
	v_rcp_f32_e32 v162, v162
	v_fma_f32 v66, v110, v183, v167
	v_mul_f32_e32 v111, v162, v111
	v_mul_f32_e32 v66, v111, v66
	v_cvt_pk_bf16_f32 v66, v66, v113
	global_store_short v[86:87], v66, off
	s_waitcnt vmcnt(15)
	v_lshlrev_b32_e32 v86, 16, v161
	v_mul_f32_e32 v87, 0x3d372713, v86
	v_mul_f32_e32 v87, v87, v86
	v_fma_f32 v87, v87, v86, v86
	v_mul_f32_e32 v87, 0x3fcc422a, v87
	v_mul_f32_e32 v87, 0xbfb8aa3b, v87
	v_exp_f32_e32 v87, v87
	s_nop 0
	v_add_f32_e32 v87, 1.0, v87
	v_rcp_f32_e32 v87, v87
	v_fma_f32 v66, v110, v184, v168
	v_mul_f32_e32 v86, v87, v86
	v_mul_f32_e32 v66, v86, v66
	v_cvt_pk_bf16_f32 v66, v66, v113
	global_store_short v[84:85], v66, off
	s_waitcnt vmcnt(15)
	v_lshlrev_b32_e32 v84, 16, v160
	v_mul_f32_e32 v85, 0x3d372713, v84
	v_mul_f32_e32 v85, v85, v84
	v_fma_f32 v85, v85, v84, v84
	v_mul_f32_e32 v85, 0x3fcc422a, v85
	v_mul_f32_e32 v85, 0xbfb8aa3b, v85
	v_exp_f32_e32 v85, v85
	s_nop 0
	v_add_f32_e32 v85, 1.0, v85
	v_rcp_f32_e32 v85, v85
	v_fma_f32 v66, v110, v185, v169
	v_mul_f32_e32 v84, v85, v84
	v_mul_f32_e32 v66, v84, v66
	v_cvt_pk_bf16_f32 v66, v66, v113
	global_store_short v[82:83], v66, off
	s_waitcnt vmcnt(15)
	v_lshlrev_b32_e32 v82, 16, v159
	v_mul_f32_e32 v83, 0x3d372713, v82
	v_mul_f32_e32 v83, v83, v82
	v_fma_f32 v83, v83, v82, v82
	v_mul_f32_e32 v83, 0x3fcc422a, v83
	v_mul_f32_e32 v83, 0xbfb8aa3b, v83
	v_exp_f32_e32 v83, v83
	s_nop 0
	v_add_f32_e32 v83, 1.0, v83
	v_rcp_f32_e32 v83, v83
	v_fma_f32 v66, v110, v186, v170
	v_mul_f32_e32 v82, v83, v82
	v_mul_f32_e32 v66, v82, v66
	v_cvt_pk_bf16_f32 v66, v66, v113
	global_store_short v[80:81], v66, off
	s_waitcnt vmcnt(15)
	v_lshlrev_b32_e32 v80, 16, v158
	v_mul_f32_e32 v81, 0x3d372713, v80
	v_mul_f32_e32 v81, v81, v80
	v_fma_f32 v81, v81, v80, v80
	v_mul_f32_e32 v81, 0x3fcc422a, v81
	v_mul_f32_e32 v81, 0xbfb8aa3b, v81
	v_exp_f32_e32 v81, v81
	s_nop 0
	v_add_f32_e32 v81, 1.0, v81
	v_rcp_f32_e32 v81, v81
	v_fma_f32 v66, v110, v187, v171
	v_mul_f32_e32 v80, v81, v80
	v_mul_f32_e32 v66, v80, v66
	v_cvt_pk_bf16_f32 v66, v66, v113
	global_store_short v[78:79], v66, off
	s_waitcnt vmcnt(15)
	v_lshlrev_b32_e32 v78, 16, v157
	v_mul_f32_e32 v79, 0x3d372713, v78
	v_mul_f32_e32 v79, v79, v78
	v_fma_f32 v79, v79, v78, v78
	v_mul_f32_e32 v79, 0x3fcc422a, v79
	v_mul_f32_e32 v79, 0xbfb8aa3b, v79
	v_exp_f32_e32 v79, v79
	s_nop 0
	v_add_f32_e32 v79, 1.0, v79
	v_rcp_f32_e32 v79, v79
	v_fma_f32 v66, v110, v188, v172
	v_mul_f32_e32 v78, v79, v78
	v_mul_f32_e32 v66, v78, v66
	v_cvt_pk_bf16_f32 v66, v66, v113
	global_store_short v[76:77], v66, off
	s_waitcnt vmcnt(15)
	v_lshlrev_b32_e32 v76, 16, v156
	v_mul_f32_e32 v77, 0x3d372713, v76
	v_mul_f32_e32 v77, v77, v76
	v_fma_f32 v77, v77, v76, v76
	v_mul_f32_e32 v77, 0x3fcc422a, v77
	v_mul_f32_e32 v77, 0xbfb8aa3b, v77
	v_exp_f32_e32 v77, v77
	s_nop 0
	v_add_f32_e32 v77, 1.0, v77
	v_rcp_f32_e32 v77, v77
	v_fma_f32 v66, v110, v189, v173
	v_mul_f32_e32 v76, v77, v76
	v_mul_f32_e32 v66, v76, v66
	v_cvt_pk_bf16_f32 v66, v66, v113
	global_store_short v[74:75], v66, off
	s_waitcnt vmcnt(15)
	v_lshlrev_b32_e32 v74, 16, v155
	v_mul_f32_e32 v75, 0x3d372713, v74
	v_mul_f32_e32 v75, v75, v74
	v_fma_f32 v75, v75, v74, v74
	v_mul_f32_e32 v75, 0x3fcc422a, v75
	v_mul_f32_e32 v75, 0xbfb8aa3b, v75
	v_exp_f32_e32 v75, v75
	s_nop 0
	v_add_f32_e32 v75, 1.0, v75
	v_rcp_f32_e32 v75, v75
	v_fma_f32 v66, v110, v208, v174
	v_mul_f32_e32 v74, v75, v74
	v_mul_f32_e32 v66, v74, v66
	v_cvt_pk_bf16_f32 v66, v66, v113
	global_store_short v[72:73], v66, off
	s_waitcnt vmcnt(15)
	v_lshlrev_b32_e32 v72, 16, v154
	v_mul_f32_e32 v73, 0x3d372713, v72
	v_mul_f32_e32 v73, v73, v72
	v_fma_f32 v73, v73, v72, v72
	v_mul_f32_e32 v73, 0x3fcc422a, v73
	v_mul_f32_e32 v73, 0xbfb8aa3b, v73
	v_exp_f32_e32 v73, v73
	s_nop 0
	v_add_f32_e32 v73, 1.0, v73
	v_rcp_f32_e32 v73, v73
	v_fma_f32 v66, v110, v209, v175
	v_mul_f32_e32 v72, v73, v72
	v_mul_f32_e32 v66, v72, v66
	v_cvt_pk_bf16_f32 v66, v66, v113
	global_store_short v[70:71], v66, off
	s_waitcnt vmcnt(15)
	v_lshlrev_b32_e32 v70, 16, v153
	v_mul_f32_e32 v71, 0x3d372713, v70
	v_mul_f32_e32 v71, v71, v70
	v_fma_f32 v71, v71, v70, v70
	v_mul_f32_e32 v71, 0x3fcc422a, v71
	v_mul_f32_e32 v71, 0xbfb8aa3b, v71
	v_exp_f32_e32 v71, v71
	s_nop 0
	v_add_f32_e32 v71, 1.0, v71
	v_rcp_f32_e32 v71, v71
	v_fma_f32 v66, v110, v210, v176
	v_mul_f32_e32 v70, v71, v70
	v_mul_f32_e32 v66, v70, v66
	v_cvt_pk_bf16_f32 v66, v66, v113
	global_store_short v[68:69], v66, off
	s_waitcnt vmcnt(15)
	v_lshlrev_b32_e32 v68, 16, v152
	v_mul_f32_e32 v69, 0x3d372713, v68
	v_mul_f32_e32 v69, v69, v68
	v_fma_f32 v69, v69, v68, v68
	v_mul_f32_e32 v69, 0x3fcc422a, v69
	v_mul_f32_e32 v69, 0xbfb8aa3b, v69
	v_exp_f32_e32 v69, v69
	s_nop 0
	v_add_f32_e32 v69, 1.0, v69
	v_rcp_f32_e32 v69, v69
	v_fma_f32 v66, v110, v211, v177
	v_mul_f32_e32 v68, v69, v68
	v_mul_f32_e32 v66, v68, v66
	v_cvt_pk_bf16_f32 v66, v66, v113
	global_store_short v[64:65], v66, off
	s_waitcnt vmcnt(15)
	v_lshlrev_b32_e32 v66, 16, v151
	v_mul_f32_e32 v67, 0x3d372713, v66
	v_mul_f32_e32 v67, v67, v66
	v_fma_f32 v67, v67, v66, v66
	v_mul_f32_e32 v67, 0x3fcc422a, v67
	v_mul_f32_e32 v67, 0xbfb8aa3b, v67
	v_exp_f32_e32 v67, v67
	s_nop 0
	v_add_f32_e32 v67, 1.0, v67
	v_rcp_f32_e32 v67, v67
	v_fma_f32 v64, v110, v212, v178
	v_mul_f32_e32 v66, v67, v66
	v_mul_f32_e32 v64, v66, v64
	v_cvt_pk_bf16_f32 v64, v64, v113
	global_store_short v[62:63], v64, off
	s_waitcnt vmcnt(15)
	v_lshlrev_b32_e32 v64, 16, v112
	v_mul_f32_e32 v65, 0x3d372713, v64
	v_mul_f32_e32 v65, v65, v64
	v_fma_f32 v65, v65, v64, v64
	v_mul_f32_e32 v65, 0x3fcc422a, v65
	v_mul_f32_e32 v65, 0xbfb8aa3b, v65
	v_exp_f32_e32 v65, v65
	s_nop 0
	v_add_f32_e32 v65, 1.0, v65
	v_rcp_f32_e32 v65, v65
	v_fma_f32 v62, v110, v213, v179
	v_mul_f32_e32 v64, v65, v64
	v_mul_f32_e32 v62, v64, v62
	v_cvt_pk_bf16_f32 v62, v62, v113
	global_store_short v[60:61], v62, off
	s_waitcnt vmcnt(15)
	v_lshlrev_b32_e32 v62, 16, v109
	v_mul_f32_e32 v63, 0x3d372713, v62
	v_mul_f32_e32 v63, v63, v62
	v_fma_f32 v63, v63, v62, v62
	v_mul_f32_e32 v63, 0x3fcc422a, v63
	v_mul_f32_e32 v63, 0xbfb8aa3b, v63
	v_exp_f32_e32 v63, v63
	s_nop 0
	v_add_f32_e32 v63, 1.0, v63
	v_rcp_f32_e32 v63, v63
	v_fma_f32 v60, v110, v252, v180
	v_mul_f32_e32 v62, v63, v62
	v_mul_f32_e32 v60, v62, v60
	v_cvt_pk_bf16_f32 v60, v60, v113
	global_store_short v[58:59], v60, off
	s_waitcnt vmcnt(15)
	v_lshlrev_b32_e32 v60, 16, v107
	v_mul_f32_e32 v61, 0x3d372713, v60
	v_mul_f32_e32 v61, v61, v60
	v_fma_f32 v61, v61, v60, v60
	v_mul_f32_e32 v61, 0x3fcc422a, v61
	v_mul_f32_e32 v61, 0xbfb8aa3b, v61
	v_exp_f32_e32 v61, v61
	s_nop 0
	v_add_f32_e32 v61, 1.0, v61
	v_rcp_f32_e32 v61, v61
	v_fma_f32 v58, v110, v253, v181
	v_mul_f32_e32 v60, v61, v60
	v_mul_f32_e32 v58, v60, v58
	v_cvt_pk_bf16_f32 v58, v58, v113
	global_store_short v[56:57], v58, off
	s_waitcnt lgkmcnt(0)
	s_barrier
	s_cbranch_scc0 .LBB0_959
.LBB0_1094:
	s_lshl_b32 s15, s11, 7
	s_mov_b64 s[0:1], s[22:23]
	v_add_u32_e32 v82, s15, v130
	s_add_u32 s8, s0, 0x7a00000
	v_max_i32_e32 v56, 3, v82
	s_addc_u32 s9, s1, 0
	v_add_u32_e32 v112, -3, v56
	v_lshl_add_u64 v[56:57], s[20:21], 0, v[112:113]
	v_mov_b64_e32 v[72:73], s[8:9]
	v_mad_u64_u32 v[58:59], s[0:1], v56, s33, v[72:73]
	v_mad_i32_i24 v59, v57, s33, v59
	v_mov_b32_e32 v107, v113
	v_lshl_add_u64 v[56:57], v[58:59], 0, v[106:107]
	v_add_co_u32_e32 v56, vcc, s74, v56
	v_max_i32_e32 v74, -1, v82
	s_nop 0
	v_addc_co_u32_e32 v57, vcc, 0, v57, vcc
	s_waitcnt vmcnt(16)
	v_mov_b32_e32 v64, v228
	v_mov_b32_e32 v65, v229
	v_mov_b32_e32 v66, v230
	v_mov_b32_e32 v67, v231
	v_or_b32_e32 v56, 1, v82
	v_max_i32_e32 v56, 3, v56
	v_add_u32_e32 v112, -3, v56
	v_lshl_add_u64 v[56:57], s[20:21], 0, v[112:113]
	v_mad_u64_u32 v[58:59], s[0:1], v56, s33, v[72:73]
	v_mad_i32_i24 v59, v57, s33, v59
	v_lshl_add_u64 v[56:57], v[58:59], 0, v[106:107]
	v_add_co_u32_e32 v56, vcc, s74, v56
	v_cmp_lt_i32_e64 s[2:3], 2, v82
	s_nop 0
	v_addc_co_u32_e32 v57, vcc, 0, v57, vcc
	v_mov_b32_e32 v68, v232
	v_mov_b32_e32 v69, v233
	v_mov_b32_e32 v70, v234
	v_mov_b32_e32 v71, v235
	v_max_i32_e32 v56, 1, v82
	v_add_u32_e32 v112, -1, v56
	v_lshl_add_u64 v[56:57], s[20:21], 0, v[112:113]
	v_max_i32_e32 v112, 0, v82
	v_lshl_add_u64 v[60:61], s[20:21], 0, v[112:113]
	v_add_u32_e32 v112, 1, v74
	v_lshl_add_u64 v[74:75], s[20:21], 0, v[112:113]
	v_mad_u64_u32 v[58:59], s[0:1], v56, s33, v[72:73]
	v_mad_u64_u32 v[62:63], s[0:1], v60, s33, v[72:73]
	v_mad_u64_u32 v[72:73], s[0:1], v74, s33, v[72:73]
	v_mad_i32_i24 v73, v75, s33, v73
	v_lshl_add_u64 v[72:73], v[72:73], 0, v[106:107]
	v_add_co_u32_e64 v72, s[0:1], s74, v72
	v_mad_i32_i24 v59, v57, s33, v59
	s_nop 0
	v_addc_co_u32_e64 v73, s[0:1], 0, v73, s[0:1]
	v_mov_b32_e32 v72, v236
	v_mov_b32_e32 v73, v237
	v_mov_b32_e32 v74, v238
	v_mov_b32_e32 v75, v239
	v_lshl_add_u64 v[56:57], v[58:59], 0, v[106:107]
	v_add_co_u32_e32 v56, vcc, s74, v56
	v_mad_i32_i24 v63, v61, s33, v63
	s_nop 0
	v_addc_co_u32_e32 v57, vcc, 0, v57, vcc
	v_lshl_add_u64 v[60:61], v[62:63], 0, v[106:107]
	v_add_co_u32_e32 v60, vcc, s74, v60
	v_mov_b32_e32 v56, v240
	v_mov_b32_e32 v57, v241
	v_mov_b32_e32 v58, v242
	v_mov_b32_e32 v59, v243
	s_nop 0
	v_addc_co_u32_e32 v61, vcc, 0, v61, vcc
	v_mov_b32_e32 v60, v244
	v_mov_b32_e32 v61, v245
	v_mov_b32_e32 v62, v246
	v_mov_b32_e32 v63, v247
	v_cmp_lt_i32_e32 vcc, -2, v82
	v_cmp_lt_i32_e64 s[0:1], -1, v82
	s_nop 0
	v_cndmask_b32_e64 v83, 0, v67, s[2:3]
	v_cndmask_b32_e64 v64, 0, v64, s[2:3]
	s_nop 0
	v_cndmask_b32_e32 v107, 0, v72, vcc
	v_cndmask_b32_e32 v109, 0, v73, vcc
	v_cndmask_b32_e32 v112, 0, v74, vcc
	v_cndmask_b32_e32 v151, 0, v75, vcc
	v_cmp_lt_i32_e32 vcc, 1, v82
	v_lshlrev_b32_e32 v74, 16, v64
	v_lshlrev_b32_e32 v72, 16, v83
	v_cndmask_b32_e32 v67, 0, v68, vcc
	v_lshlrev_b32_e32 v75, 16, v67
	v_pk_mul_f32 v[76:77], v[104:105], v[74:75]
	v_cndmask_b32_e32 v84, 0, v71, vcc
	v_add_f32_e32 v68, v48, v76
	v_add_f32_e32 v74, v68, v77
	v_and_b32_e32 v77, 0xffff0000, v67
	v_and_b32_e32 v76, 0xffff0000, v64
	v_pk_mul_f32 v[80:81], v[40:41], v[76:77]
	v_cndmask_b32_e64 v67, 0, v65, s[2:3]
	v_add_f32_e32 v64, v49, v80
	v_cndmask_b32_e32 v71, 0, v69, vcc
	v_add_f32_e32 v152, v64, v81
	v_lshlrev_b32_e32 v65, 16, v71
	v_lshlrev_b32_e32 v64, 16, v67
	v_pk_mul_f32 v[68:69], v[100:101], v[64:65]
	v_lshlrev_b32_e32 v73, 16, v84
	v_add_f32_e32 v64, v50, v68
	v_add_f32_e32 v64, v64, v69
	v_and_b32_e32 v69, 0xffff0000, v71
	v_and_b32_e32 v68, 0xffff0000, v67
	v_pk_mul_f32 v[78:79], v[92:93], v[72:73]
	v_pk_mul_f32 v[80:81], v[42:43], v[68:69]
	v_add_f32_e32 v72, v54, v78
	v_add_f32_e32 v67, v51, v80
	v_cndmask_b32_e64 v78, 0, v66, s[2:3]
	v_cndmask_b32_e32 v80, 0, v70, vcc
	v_add_f32_e32 v153, v67, v81
	v_lshlrev_b32_e32 v67, 16, v80
	v_lshlrev_b32_e32 v66, 16, v78
	v_pk_mul_f32 v[70:71], v[96:97], v[66:67]
	v_cmp_lt_i32_e32 vcc, 0, v82
	v_add_f32_e32 v66, v52, v70
	v_add_f32_e32 v66, v66, v71
	v_and_b32_e32 v71, 0xffff0000, v80
	v_and_b32_e32 v70, 0xffff0000, v78
	v_pk_mul_f32 v[80:81], v[36:37], v[70:71]
	v_add_f32_e32 v72, v72, v79
	v_add_f32_e32 v78, v53, v80
	v_add_f32_e32 v154, v78, v81
	v_and_b32_e32 v79, 0xffff0000, v84
	v_and_b32_e32 v78, 0xffff0000, v83
	s_nop 0
	v_cndmask_b32_e64 v60, 0, v60, s[0:1]
	v_cndmask_b32_e32 v56, 0, v56, vcc
	v_pk_mul_f32 v[80:81], v[38:39], v[78:79]
	v_lshlrev_b32_e32 v84, 16, v56
	v_lshlrev_b32_e32 v85, 16, v60
	v_add_f32_e32 v80, v55, v80
	v_cndmask_b32_e64 v156, 0, v63, s[0:1]
	v_cndmask_b32_e32 v59, 0, v59, vcc
	v_pk_mul_f32 v[86:87], v[102:103], v[84:85]
	v_add_f32_e32 v155, v80, v81
	v_lshlrev_b32_e32 v80, 16, v59
	v_lshlrev_b32_e32 v81, 16, v156
	v_add_f32_e32 v63, v74, v86
	v_pk_mul_f32 v[82:83], v[90:91], v[80:81]
	v_add_f32_e32 v74, v63, v87
	v_and_b32_e32 v87, 0xffff0000, v60
	v_and_b32_e32 v86, 0xffff0000, v56
	v_add_f32_e32 v72, v72, v82
	v_pk_mul_f32 v[110:111], v[44:45], v[86:87]
	v_cndmask_b32_e64 v63, 0, v61, s[0:1]
	v_cndmask_b32_e32 v82, 0, v57, vcc
	v_add_f32_e32 v56, v152, v110
	v_lshlrev_b32_e32 v60, 16, v82
	v_lshlrev_b32_e32 v61, 16, v63
	v_add_f32_e32 v157, v56, v111
	v_pk_mul_f32 v[56:57], v[98:99], v[60:61]
	v_and_b32_e32 v111, 0xffff0000, v63
	v_add_f32_e32 v56, v64, v56
	v_and_b32_e32 v110, 0xffff0000, v82
	v_add_f32_e32 v64, v56, v57
	v_pk_mul_f32 v[56:57], v[46:47], v[110:111]
	v_cndmask_b32_e64 v82, 0, v62, s[0:1]
	v_cndmask_b32_e32 v58, 0, v58, vcc
	v_add_f32_e32 v56, v153, v56
	v_lshlrev_b32_e32 v62, 16, v58
	v_lshlrev_b32_e32 v63, 16, v82
	v_add_f32_e32 v158, v56, v57
	v_pk_mul_f32 v[56:57], v[94:95], v[62:63]
	v_and_b32_e32 v153, 0xffff0000, v82
	v_add_f32_e32 v56, v66, v56
	v_and_b32_e32 v152, 0xffff0000, v58
	v_add_f32_e32 v66, v56, v57
	v_pk_mul_f32 v[56:57], v[32:33], v[152:153]
	v_add_f32_e32 v72, v72, v83
	v_add_f32_e32 v56, v154, v56
	v_and_b32_e32 v83, 0xffff0000, v156
	v_and_b32_e32 v82, 0xffff0000, v59
	v_add_f32_e32 v58, v56, v57
	v_pk_mul_f32 v[56:57], v[34:35], v[82:83]
	s_add_u32 s0, s12, s15
	v_add_f32_e32 v56, v155, v56
	v_add_f32_e32 v59, v56, v57
	v_cvt_pk_bf16_f32 v56, v74, v157
	v_cvt_pk_bf16_f32 v57, v64, v158
	v_cvt_pk_bf16_f32 v58, v66, v58
	v_cvt_pk_bf16_f32 v59, v72, v59
	ds_write_b128 v142, v[56:59] offset:18432
	v_pk_mov_b32 v[56:57], v[74:75], v[84:85] op_sel:[1,0]
	v_and_b32_e32 v59, 0xffff0000, v107
	v_pk_mul_f32 v[56:57], v[104:105], v[56:57]
	v_and_b32_e32 v75, 0xffff0000, v151
	v_add_f32_e32 v56, v48, v56
	v_add_f32_e32 v58, v56, v57
	v_pk_mov_b32 v[56:57], v[76:77], v[86:87] op_sel:[1,0]
	s_addc_u32 s1, s13, 0
	v_pk_mul_f32 v[56:57], v[40:41], v[56:57]
	s_mulk_i32 s1, 0x2400
	v_add_f32_e32 v56, v49, v56
	v_add_f32_e32 v64, v56, v57
	v_pk_mov_b32 v[56:57], v[64:65], v[60:61] op_sel:[1,0]
	v_lshlrev_b32_e32 v65, 16, v109
	v_pk_mul_f32 v[56:57], v[100:101], v[56:57]
	s_mul_hi_u32 s2, s0, 0x2400
	v_add_f32_e32 v56, v50, v56
	v_add_f32_e32 v60, v56, v57
	v_pk_mov_b32 v[56:57], v[68:69], v[110:111] op_sel:[1,0]
	v_lshlrev_b32_e32 v69, 16, v112
	v_pk_mul_f32 v[56:57], v[42:43], v[56:57]
	s_add_i32 s2, s2, s1
	v_add_f32_e32 v56, v51, v56
	v_add_f32_e32 v68, v56, v57
	v_pk_mov_b32 v[56:57], v[66:67], v[62:63] op_sel:[1,0]
	v_and_b32_e32 v67, 0xffff0000, v109
	v_pk_mul_f32 v[56:57], v[96:97], v[56:57]
	v_mov_b32_e32 v66, v111
	v_add_f32_e32 v56, v52, v56
	v_add_f32_e32 v62, v56, v57
	v_pk_mov_b32 v[56:57], v[70:71], v[152:153] op_sel:[1,0]
	v_and_b32_e32 v71, 0xffff0000, v112
	v_pk_mul_f32 v[56:57], v[36:37], v[56:57]
	v_mov_b32_e32 v70, v153
	v_add_f32_e32 v56, v53, v56
	v_add_f32_e32 v72, v56, v57
	v_pk_mov_b32 v[56:57], v[72:73], v[80:81] op_sel:[1,0]
	v_lshlrev_b32_e32 v73, 16, v151
	v_pk_mul_f32 v[56:57], v[92:93], v[56:57]
	v_add_u32_e32 v80, v132, v131
	v_add_f32_e32 v56, v54, v56
	v_add_f32_e32 v74, v56, v57
	v_pk_mov_b32 v[56:57], v[78:79], v[82:83] op_sel:[1,0]
	s_mulk_i32 s0, 0x2400
	v_pk_mul_f32 v[56:57], v[38:39], v[56:57]
	s_add_u32 s0, s8, s0
	v_add_f32_e32 v56, v55, v56
	v_add_f32_e32 v76, v56, v57
	v_lshlrev_b32_e32 v57, 16, v107
	v_mov_b32_e32 v56, v85
	v_pk_mul_f32 v[56:57], v[102:103], v[56:57]
	s_addc_u32 s1, s9, s2
	v_add_f32_e32 v56, v58, v56
	v_mov_b32_e32 v58, v87
	v_add_f32_e32 v77, v56, v57
	v_pk_mul_f32 v[56:57], v[44:45], v[58:59]
	s_add_u32 s0, s0, s14
	v_add_f32_e32 v56, v64, v56
	v_mov_b32_e32 v64, v61
	v_add_f32_e32 v58, v56, v57
	v_pk_mul_f32 v[56:57], v[98:99], v[64:65]
	s_addc_u32 s1, s1, 0
	v_add_f32_e32 v56, v60, v56
	v_add_f32_e32 v59, v56, v57
	v_pk_mul_f32 v[56:57], v[46:47], v[66:67]
	v_mov_b32_e32 v109, v113
	v_add_f32_e32 v56, v68, v56
	v_mov_b32_e32 v68, v63
	v_add_f32_e32 v60, v56, v57
	v_pk_mul_f32 v[56:57], v[94:95], v[68:69]
	s_nop 0
	v_add_f32_e32 v56, v62, v56
	v_add_f32_e32 v61, v56, v57
	v_pk_mul_f32 v[56:57], v[32:33], v[70:71]
	s_nop 0
	v_add_f32_e32 v56, v72, v56
	v_mov_b32_e32 v72, v81
	v_add_f32_e32 v62, v56, v57
	v_pk_mul_f32 v[56:57], v[90:91], v[72:73]
	s_nop 0
	v_add_f32_e32 v56, v74, v56
	v_mov_b32_e32 v74, v83
	v_add_f32_e32 v63, v56, v57
	v_pk_mul_f32 v[56:57], v[34:35], v[74:75]
	s_nop 0
	v_add_f32_e32 v56, v76, v56
	v_add_f32_e32 v64, v56, v57
	v_cvt_pk_bf16_f32 v56, v77, v58
	v_cvt_pk_bf16_f32 v57, v59, v60
	v_cvt_pk_bf16_f32 v58, v61, v62
	v_cvt_pk_bf16_f32 v59, v63, v64
	ds_write_b128 v143, v[56:59] offset:18432
	s_waitcnt lgkmcnt(0)
	s_barrier
	s_add_i32 s98, s11, 1
	s_min_u32 s98, s98, 15
	s_lshl_b32 s98, s98, 7
	v_add_u32_e32 v172, s98, v130
	v_add_u32_e32 v173, 0x7a01c00, v106
	v_add_u32_e32 v174, -3, v172
	v_max_i32_e32 v174, 0, v174
	v_add_u32_e32 v174, s20, v174
	v_mad_u32_u24 v174, v174, s33, v173
	global_load_dwordx4 v[228:231], v174, s[22:23]
	v_add_u32_e32 v175, -2, v172
	v_max_i32_e32 v175, 0, v175
	v_add_u32_e32 v175, s20, v175
	v_mad_u32_u24 v175, v175, s33, v173
	global_load_dwordx4 v[232:235], v175, s[22:23]
	v_add_u32_e32 v176, 1, v172
	v_max_i32_e32 v176, 0, v176
	v_add_u32_e32 v176, s20, v176
	v_mad_u32_u24 v176, v176, s33, v173
	global_load_dwordx4 v[236:239], v176, s[22:23]
	v_add_u32_e32 v177, -1, v172
	v_max_i32_e32 v177, 0, v177
	v_add_u32_e32 v177, s20, v177
	v_mad_u32_u24 v177, v177, s33, v173
	global_load_dwordx4 v[240:243], v177, s[22:23]
	v_add_u32_e32 v178, 0, v172
	v_max_i32_e32 v178, 0, v178
	v_add_u32_e32 v178, s20, v178
	v_mad_u32_u24 v178, v178, s33, v173
	global_load_dwordx4 v[244:247], v178, s[22:23]
	ds_read_b128 v[56:59], v80 offset:18432
	ds_read_b128 v[60:63], v144
	ds_read_b128 v[68:71], v144 offset:2304
	ds_read_b128 v[76:79], v144 offset:4608
	ds_read_b128 v[72:75], v144 offset:11520
	s_waitcnt lgkmcnt(1)
	v_mfma_f32_16x16x32_bf16 v[152:155], v[76:79], v[56:59], 0
	ds_read_b128 v[76:79], v144 offset:13824
	ds_read_b128 v[64:67], v144 offset:9216
	s_waitcnt lgkmcnt(1)
	v_mfma_f32_16x16x32_bf16 v[156:159], v[76:79], v[56:59], 0
	ds_read_b128 v[76:79], v144 offset:6912
	s_waitcnt lgkmcnt(0)
	v_mfma_f32_16x16x32_bf16 v[160:163], v[76:79], v[56:59], 0
	ds_read_b128 v[76:79], v144 offset:16128
	v_mfma_f32_16x16x32_bf16 v[60:63], v[60:63], v[56:59], 0
	v_mfma_f32_16x16x32_bf16 v[64:67], v[64:67], v[56:59], 0
	v_mfma_f32_16x16x32_bf16 v[68:71], v[68:71], v[56:59], 0
	v_mfma_f32_16x16x32_bf16 v[72:75], v[72:75], v[56:59], 0
	s_waitcnt lgkmcnt(0)
	v_mfma_f32_16x16x32_bf16 v[164:167], v[76:79], v[56:59], 0
	ds_read_b128 v[168:171], v80 offset:18496
	ds_read_b128 v[56:59], v144 offset:64
	ds_read_b64 v[110:111], v145 offset:18432
	s_waitcnt lgkmcnt(1)
	v_mfma_f32_16x16x32_bf16 v[84:87], v[56:59], v[168:171], v[60:63]
	ds_read_b128 v[56:59], v144 offset:9280
	s_nop 1
	ds_read_b128 v[60:63], v144 offset:16192
	s_waitcnt lgkmcnt(1)
	v_mfma_f32_16x16x32_bf16 v[80:83], v[56:59], v[168:171], v[64:67]
	ds_read_b128 v[56:59], v144 offset:2368
	s_nop 0
	v_add_f32_e32 v84, v0, v84
	v_mul_f32_e32 v84, 0xbfb8aa3b, v84
	s_waitcnt lgkmcnt(0)
	v_mfma_f32_16x16x32_bf16 v[76:79], v[56:59], v[168:171], v[68:71]
	ds_read_b128 v[56:59], v144 offset:11584
	v_exp_f32_e32 v84, v84
	v_add_f32_e32 v80, v4, v80
	v_mul_f32_e32 v80, 0xbfb8aa3b, v80
	v_exp_f32_e32 v80, v80
	v_add_f32_e32 v84, 1.0, v84
	v_rcp_f32_e32 v107, v84
	s_waitcnt lgkmcnt(0)
	v_mfma_f32_16x16x32_bf16 v[72:75], v[56:59], v[168:171], v[72:75]
	ds_read_b128 v[56:59], v144 offset:4672
	v_add_f32_e32 v80, 1.0, v80
	v_mul_f32_e32 v107, v127, v107
	v_rcp_f32_e32 v84, v80
	v_mul_f32_e32 v80, 0x3fb8aa3b, v107
	v_add_f32_e32 v107, v107, v107
	v_mul_f32_e32 v107, 0x3fb8aa3b, v107
	v_add_f32_e32 v85, v1, v85
	v_exp_f32_e32 v107, v107
	v_mul_f32_e32 v85, 0xbfb8aa3b, v85
	v_exp_f32_e32 v85, v85
	v_add_f32_e32 v81, v5, v81
	v_sub_f32_e32 v107, 1.0, v107
	v_max_f32_e32 v107, 0, v107
	v_add_f32_e32 v85, 1.0, v85
	v_mul_f32_e32 v81, 0xbfb8aa3b, v81
	s_waitcnt lgkmcnt(0)
	v_mfma_f32_16x16x32_bf16 v[68:71], v[56:59], v[168:171], v[152:155]
	v_exp_f32_e32 v81, v81
	v_add_f32_e32 v86, v2, v86
	v_mul_f32_e32 v86, 0xbfb8aa3b, v86
	v_sqrt_f32_e32 v152, v107
	v_rcp_f32_e32 v107, v85
	v_add_f32_e32 v81, 1.0, v81
	v_rcp_f32_e32 v85, v81
	v_exp_f32_e32 v86, v86
	v_mul_f32_e32 v107, v126, v107
	v_mul_f32_e32 v81, 0x3fb8aa3b, v107
	v_add_f32_e32 v107, v107, v107
	v_mul_f32_e32 v107, 0x3fb8aa3b, v107
	v_exp_f32_e32 v107, v107
	v_add_f32_e32 v82, v6, v82
	v_add_f32_e32 v86, 1.0, v86
	v_mul_f32_e32 v82, 0xbfb8aa3b, v82
	v_sub_f32_e32 v107, 1.0, v107
	v_max_f32_e32 v107, 0, v107
	v_sqrt_f32_e32 v153, v107
	v_rcp_f32_e32 v107, v86
	v_exp_f32_e32 v82, v82
	v_add_f32_e32 v87, v3, v87
	v_mul_f32_e32 v87, 0xbfb8aa3b, v87
	v_mul_f32_e32 v107, v125, v107
	v_add_f32_e32 v82, 1.0, v82
	v_rcp_f32_e32 v86, v82
	v_mul_f32_e32 v82, 0x3fb8aa3b, v107
	v_add_f32_e32 v107, v107, v107
	v_mul_f32_e32 v107, 0x3fb8aa3b, v107
	v_exp_f32_e32 v107, v107
	v_exp_f32_e32 v87, v87
	v_add_f32_e32 v83, v7, v83
	v_mul_f32_e32 v83, 0xbfb8aa3b, v83
	v_sub_f32_e32 v107, 1.0, v107
	v_max_f32_e32 v107, 0, v107
	v_add_f32_e32 v87, 1.0, v87
	v_pk_mul_f32 v[84:85], v[84:85], v[152:153]
	v_sqrt_f32_e32 v152, v107
	v_rcp_f32_e32 v107, v87
	v_exp_f32_e32 v83, v83
	ds_read_b128 v[56:59], v144 offset:13888
	v_exp_f32_e32 v80, v80
	v_mul_f32_e32 v107, v124, v107
	v_add_f32_e32 v83, 1.0, v83
	v_rcp_f32_e32 v87, v83
	v_mul_f32_e32 v83, 0x3fb8aa3b, v107
	v_add_f32_e32 v107, v107, v107
	v_mul_f32_e32 v107, 0x3fb8aa3b, v107
	v_exp_f32_e32 v107, v107
	v_exp_f32_e32 v81, v81
	v_exp_f32_e32 v82, v82
	v_exp_f32_e32 v83, v83
	v_sub_f32_e32 v107, 1.0, v107
	v_max_f32_e32 v107, 0, v107
	v_sqrt_f32_e32 v153, v107
	v_add_f32_e32 v76, v8, v76
	v_add_f32_e32 v77, v9, v77
	v_mul_f32_e32 v76, 0xbfb8aa3b, v76
	v_mul_f32_e32 v77, 0xbfb8aa3b, v77
	v_exp_f32_e32 v76, v76
	v_exp_f32_e32 v77, v77
	v_lshlrev_b32_e32 v154, 16, v110
	v_and_b32_e32 v155, 0xffff0000, v110
	v_lshlrev_b32_e32 v110, 16, v111
	v_and_b32_e32 v111, 0xffff0000, v111
	v_pk_mul_f32 v[86:87], v[86:87], v[152:153]
	v_add_u32_e32 v107, v133, v137
	s_waitcnt lgkmcnt(0)
	v_mfma_f32_16x16x32_bf16 v[64:67], v[56:59], v[168:171], v[156:159]
	ds_read_b128 v[56:59], v144 offset:6976
	v_pk_mul_f32 v[84:85], v[84:85], v[154:155]
	v_pk_mul_f32 v[86:87], v[86:87], v[110:111]
	ds_write_b128 v107, v[80:83] offset:36864
	v_add_u32_e32 v80, v134, v137
	v_add_f32_e32 v78, v10, v78
	ds_write_b128 v80, v[84:87]
	v_add_f32_e32 v72, v12, v72
	v_add_f32_e32 v73, v13, v73
	v_mul_f32_e32 v78, 0xbfb8aa3b, v78
	ds_read_b64 v[80:81], v146 offset:18432
	v_add_f32_e32 v76, 1.0, v76
	v_mul_f32_e32 v72, 0xbfb8aa3b, v72
	v_add_f32_e32 v77, 1.0, v77
	v_mul_f32_e32 v73, 0xbfb8aa3b, v73
	v_exp_f32_e32 v78, v78
	v_rcp_f32_e32 v82, v76
	v_exp_f32_e32 v72, v72
	v_rcp_f32_e32 v83, v77
	v_exp_f32_e32 v73, v73
	v_add_f32_e32 v74, v14, v74
	v_add_f32_e32 v78, 1.0, v78
	v_mul_f32_e32 v74, 0xbfb8aa3b, v74
	v_add_f32_e32 v72, 1.0, v72
	v_mul_f32_e32 v82, v123, v82
	v_add_f32_e32 v73, 1.0, v73
	v_mul_f32_e32 v83, v122, v83
	s_waitcnt lgkmcnt(0)
	v_lshlrev_b32_e32 v84, 16, v80
	v_and_b32_e32 v85, 0xffff0000, v80
	v_rcp_f32_e32 v80, v78
	v_exp_f32_e32 v74, v74
	v_rcp_f32_e32 v76, v72
	v_mul_f32_e32 v72, 0x3fb8aa3b, v82
	v_add_f32_e32 v82, v82, v82
	v_rcp_f32_e32 v77, v73
	v_mul_f32_e32 v73, 0x3fb8aa3b, v83
	v_add_f32_e32 v83, v83, v83
	v_mul_f32_e32 v82, 0x3fb8aa3b, v82
	v_mul_f32_e32 v83, 0x3fb8aa3b, v83
	v_exp_f32_e32 v82, v82
	v_exp_f32_e32 v83, v83
	v_add_f32_e32 v74, 1.0, v74
	v_mul_f32_e32 v80, v121, v80
	v_rcp_f32_e32 v78, v74
	v_mul_f32_e32 v74, 0x3fb8aa3b, v80
	v_add_f32_e32 v80, v80, v80
	v_mul_f32_e32 v80, 0x3fb8aa3b, v80
	v_add_f32_e32 v79, v11, v79
	v_sub_f32_e32 v82, 1.0, v82
	v_sub_f32_e32 v83, 1.0, v83
	v_exp_f32_e32 v80, v80
	v_mul_f32_e32 v79, 0xbfb8aa3b, v79
	v_max_f32_e32 v82, 0, v82
	v_max_f32_e32 v83, 0, v83
	v_exp_f32_e32 v79, v79
	v_sqrt_f32_e32 v82, v82
	v_sqrt_f32_e32 v83, v83
	v_sub_f32_e32 v80, 1.0, v80
	v_add_f32_e32 v75, v15, v75
	v_max_f32_e32 v80, 0, v80
	v_add_f32_e32 v79, 1.0, v79
	v_mul_f32_e32 v75, 0xbfb8aa3b, v75
	v_pk_mul_f32 v[76:77], v[76:77], v[82:83]
	v_sqrt_f32_e32 v82, v80
	v_rcp_f32_e32 v80, v79
	v_exp_f32_e32 v75, v75
	v_exp_f32_e32 v72, v72
	v_exp_f32_e32 v73, v73
	v_mul_f32_e32 v80, v120, v80
	v_add_f32_e32 v75, 1.0, v75
	v_rcp_f32_e32 v79, v75
	v_mul_f32_e32 v75, 0x3fb8aa3b, v80
	v_add_f32_e32 v80, v80, v80
	v_mul_f32_e32 v80, 0x3fb8aa3b, v80
	v_exp_f32_e32 v80, v80
	v_exp_f32_e32 v74, v74
	v_exp_f32_e32 v75, v75
	v_add_f32_e32 v68, v16, v68
	v_sub_f32_e32 v80, 1.0, v80
	v_max_f32_e32 v80, 0, v80
	v_sqrt_f32_e32 v83, v80
	v_add_f32_e32 v69, v17, v69
	v_mul_f32_e32 v68, 0xbfb8aa3b, v68
	v_mul_f32_e32 v69, 0xbfb8aa3b, v69
	v_lshlrev_b32_e32 v80, 16, v81
	v_and_b32_e32 v81, 0xffff0000, v81
	v_pk_mul_f32 v[78:79], v[78:79], v[82:83]
	v_exp_f32_e32 v68, v68
	v_exp_f32_e32 v69, v69
	v_pk_mul_f32 v[78:79], v[78:79], v[80:81]
	v_add_u32_e32 v80, v133, v138
	v_pk_mul_f32 v[76:77], v[76:77], v[84:85]
	ds_write_b128 v80, v[72:75] offset:36864
	v_add_u32_e32 v72, v134, v138
	v_add_f32_e32 v70, v18, v70
	ds_write_b128 v72, v[76:79]
	v_add_f32_e32 v64, v20, v64
	v_add_f32_e32 v65, v21, v65
	v_mul_f32_e32 v70, 0xbfb8aa3b, v70
	ds_read_b64 v[72:73], v147 offset:18432
	v_add_f32_e32 v68, 1.0, v68
	v_mul_f32_e32 v64, 0xbfb8aa3b, v64
	v_add_f32_e32 v69, 1.0, v69
	v_mul_f32_e32 v65, 0xbfb8aa3b, v65
	v_exp_f32_e32 v70, v70
	v_rcp_f32_e32 v74, v68
	v_exp_f32_e32 v64, v64
	v_rcp_f32_e32 v75, v69
	v_exp_f32_e32 v65, v65
	v_add_f32_e32 v66, v22, v66
	v_add_f32_e32 v70, 1.0, v70
	v_mul_f32_e32 v66, 0xbfb8aa3b, v66
	v_add_f32_e32 v64, 1.0, v64
	v_mul_f32_e32 v74, v119, v74
	v_add_f32_e32 v65, 1.0, v65
	v_mul_f32_e32 v75, v118, v75
	s_waitcnt lgkmcnt(0)
	v_lshlrev_b32_e32 v76, 16, v72
	v_and_b32_e32 v77, 0xffff0000, v72
	v_rcp_f32_e32 v72, v70
	v_exp_f32_e32 v66, v66
	v_rcp_f32_e32 v68, v64
	v_mul_f32_e32 v64, 0x3fb8aa3b, v74
	v_add_f32_e32 v74, v74, v74
	v_rcp_f32_e32 v69, v65
	v_mul_f32_e32 v65, 0x3fb8aa3b, v75
	v_add_f32_e32 v75, v75, v75
	v_mul_f32_e32 v74, 0x3fb8aa3b, v74
	v_mul_f32_e32 v75, 0x3fb8aa3b, v75
	v_exp_f32_e32 v74, v74
	v_exp_f32_e32 v75, v75
	v_add_f32_e32 v66, 1.0, v66
	v_mul_f32_e32 v72, v117, v72
	v_rcp_f32_e32 v70, v66
	v_mul_f32_e32 v66, 0x3fb8aa3b, v72
	v_add_f32_e32 v72, v72, v72
	v_mul_f32_e32 v72, 0x3fb8aa3b, v72
	v_add_f32_e32 v71, v19, v71
	v_sub_f32_e32 v74, 1.0, v74
	v_sub_f32_e32 v75, 1.0, v75
	v_exp_f32_e32 v72, v72
	v_mul_f32_e32 v71, 0xbfb8aa3b, v71
	v_max_f32_e32 v74, 0, v74
	v_max_f32_e32 v75, 0, v75
	v_exp_f32_e32 v71, v71
	v_sqrt_f32_e32 v74, v74
	v_sqrt_f32_e32 v75, v75
	v_sub_f32_e32 v72, 1.0, v72
	v_add_f32_e32 v67, v23, v67
	v_max_f32_e32 v72, 0, v72
	v_add_f32_e32 v71, 1.0, v71
	v_mul_f32_e32 v67, 0xbfb8aa3b, v67
	v_pk_mul_f32 v[68:69], v[68:69], v[74:75]
	v_sqrt_f32_e32 v74, v72
	v_rcp_f32_e32 v72, v71
	v_exp_f32_e32 v67, v67
	v_mfma_f32_16x16x32_bf16 v[56:59], v[56:59], v[168:171], v[160:163]
	v_exp_f32_e32 v64, v64
	v_mul_f32_e32 v72, v116, v72
	v_add_f32_e32 v67, 1.0, v67
	v_rcp_f32_e32 v71, v67
	v_mul_f32_e32 v67, 0x3fb8aa3b, v72
	v_add_f32_e32 v72, v72, v72
	v_mul_f32_e32 v72, 0x3fb8aa3b, v72
	v_exp_f32_e32 v72, v72
	v_add_f32_e32 v56, v24, v56
	v_add_f32_e32 v57, v25, v57
	v_mul_f32_e32 v56, 0xbfb8aa3b, v56
	v_sub_f32_e32 v72, 1.0, v72
	v_max_f32_e32 v72, 0, v72
	v_mul_f32_e32 v57, 0xbfb8aa3b, v57
	v_sqrt_f32_e32 v75, v72
	v_exp_f32_e32 v56, v56
	v_exp_f32_e32 v57, v57
	v_exp_f32_e32 v65, v65
	v_exp_f32_e32 v66, v66
	v_exp_f32_e32 v67, v67
	v_add_f32_e32 v58, v26, v58
	v_mul_f32_e32 v58, 0xbfb8aa3b, v58
	v_lshlrev_b32_e32 v72, 16, v73
	v_and_b32_e32 v73, 0xffff0000, v73
	v_pk_mul_f32 v[70:71], v[70:71], v[74:75]
	v_add_f32_e32 v56, 1.0, v56
	v_add_f32_e32 v57, 1.0, v57
	v_exp_f32_e32 v58, v58
	v_pk_mul_f32 v[70:71], v[70:71], v[72:73]
	v_add_u32_e32 v72, v133, v139
	v_rcp_f32_e32 v56, v56
	v_rcp_f32_e32 v57, v57
	v_pk_mul_f32 v[68:69], v[68:69], v[76:77]
	ds_write_b128 v72, v[64:67] offset:36864
	v_add_u32_e32 v64, v134, v139
	v_mfma_f32_16x16x32_bf16 v[60:63], v[60:63], v[168:171], v[164:167]
	ds_write_b128 v64, v[68:71]
	ds_read_b64 v[64:65], v148 offset:18432
	v_add_f32_e32 v58, 1.0, v58
	v_mul_f32_e32 v66, v115, v56
	v_mul_f32_e32 v67, v114, v57
	v_rcp_f32_e32 v58, v58
	v_mul_f32_e32 v56, 0x3fb8aa3b, v66
	v_add_f32_e32 v66, v66, v66
	v_mul_f32_e32 v57, 0x3fb8aa3b, v67
	v_add_f32_e32 v67, v67, v67
	v_add_f32_e32 v60, v28, v60
	v_mul_f32_e32 v66, 0x3fb8aa3b, v66
	v_add_f32_e32 v61, v29, v61
	v_mul_f32_e32 v67, 0x3fb8aa3b, v67
	v_add_f32_e32 v59, v27, v59
	v_mul_f32_e32 v60, 0xbfb8aa3b, v60
	v_exp_f32_e32 v66, v66
	v_mul_f32_e32 v61, 0xbfb8aa3b, v61
	v_exp_f32_e32 v67, v67
	v_mul_f32_e32 v59, 0xbfb8aa3b, v59
	v_exp_f32_e32 v60, v60
	v_exp_f32_e32 v61, v61
	s_waitcnt lgkmcnt(0)
	v_lshlrev_b32_e32 v68, 16, v64
	v_and_b32_e32 v69, 0xffff0000, v64
	v_mul_f32_e32 v64, v89, v58
	v_exp_f32_e32 v59, v59
	v_mul_f32_e32 v58, 0x3fb8aa3b, v64
	v_add_f32_e32 v64, v64, v64
	v_mul_f32_e32 v64, 0x3fb8aa3b, v64
	v_sub_f32_e32 v66, 1.0, v66
	v_sub_f32_e32 v67, 1.0, v67
	v_exp_f32_e32 v64, v64
	v_add_f32_e32 v60, 1.0, v60
	v_max_f32_e32 v66, 0, v66
	v_add_f32_e32 v61, 1.0, v61
	v_max_f32_e32 v67, 0, v67
	v_add_f32_e32 v59, 1.0, v59
	v_rcp_f32_e32 v60, v60
	v_sqrt_f32_e32 v66, v66
	v_rcp_f32_e32 v61, v61
	v_sqrt_f32_e32 v67, v67
	v_rcp_f32_e32 v59, v59
	v_sub_f32_e32 v64, 1.0, v64
	v_max_f32_e32 v64, 0, v64
	v_pk_mul_f32 v[60:61], v[60:61], v[66:67]
	v_sqrt_f32_e32 v66, v64
	v_mul_f32_e32 v64, v128, v59
	v_mul_f32_e32 v59, 0x3fb8aa3b, v64
	v_add_f32_e32 v64, v64, v64
	v_add_f32_e32 v62, v30, v62
	v_add_f32_e32 v63, v31, v63
	v_mul_f32_e32 v64, 0x3fb8aa3b, v64
	v_mul_f32_e32 v62, 0xbfb8aa3b, v62
	v_mul_f32_e32 v63, 0xbfb8aa3b, v63
	v_exp_f32_e32 v64, v64
	v_exp_f32_e32 v62, v62
	v_exp_f32_e32 v63, v63
	v_exp_f32_e32 v56, v56
	v_sub_f32_e32 v64, 1.0, v64
	v_add_f32_e32 v62, 1.0, v62
	v_add_f32_e32 v63, 1.0, v63
	v_max_f32_e32 v64, 0, v64
	v_rcp_f32_e32 v62, v62
	v_rcp_f32_e32 v63, v63
	v_sqrt_f32_e32 v67, v64
	v_exp_f32_e32 v57, v57
	v_exp_f32_e32 v58, v58
	v_exp_f32_e32 v59, v59
	v_lshlrev_b32_e32 v64, 16, v65
	v_and_b32_e32 v65, 0xffff0000, v65
	v_pk_mul_f32 v[62:63], v[62:63], v[66:67]
	v_pk_mul_f32 v[60:61], v[60:61], v[68:69]
	v_pk_mul_f32 v[62:63], v[62:63], v[64:65]
	v_add_u32_e32 v64, v133, v140
	ds_write_b128 v64, v[56:59] offset:36864
	v_add_u32_e32 v56, v134, v140
	v_lshl_add_u64 v[66:67], s[0:1], 0, v[108:109]
	ds_write_b128 v56, v[60:63]
	v_add_co_u32_e32 v56, vcc, s16, v66
	s_waitcnt lgkmcnt(0)
	s_barrier
	s_nop 0
	v_addc_co_u32_e32 v57, vcc, 0, v67, vcc
	global_load_ushort v163, v108, s[0:1] offset:2048
	global_load_ushort v162, v[56:57], off offset:3072
	s_movk_i32 s0, 0x5000
	v_add_co_u32_e32 v56, vcc, s0, v66
	s_movk_i32 s0, 0x7000
	s_nop 0
	v_addc_co_u32_e32 v57, vcc, 0, v67, vcc
	global_load_ushort v161, v[56:57], off
	v_add_co_u32_e32 v56, vcc, s0, v66
	s_mov_b32 s0, 0x9000
	s_nop 0
	v_addc_co_u32_e32 v57, vcc, 0, v67, vcc
	global_load_ushort v160, v[56:57], off offset:1024
	v_add_co_u32_e32 v56, vcc, s0, v66
	s_mov_b32 s0, 0xb000
	s_nop 0
	v_addc_co_u32_e32 v57, vcc, 0, v67, vcc
	global_load_ushort v159, v[56:57], off offset:2048
	v_add_co_u32_e32 v56, vcc, s0, v66
	s_mov_b32 s0, 0xe000
	s_nop 0
	v_addc_co_u32_e32 v57, vcc, 0, v67, vcc
	global_load_ushort v158, v[56:57], off offset:3072
	v_add_co_u32_e32 v56, vcc, s0, v66
	s_mov_b32 s0, 0x10000
	s_nop 0
	v_addc_co_u32_e32 v57, vcc, 0, v67, vcc
	global_load_ushort v157, v[56:57], off
	v_add_co_u32_e32 v56, vcc, s0, v66
	s_mov_b32 s0, 0x12000
	s_nop 0
	v_addc_co_u32_e32 v57, vcc, 0, v67, vcc
	global_load_ushort v156, v[56:57], off offset:1024
	v_add_co_u32_e32 v56, vcc, s0, v66
	s_mov_b32 s0, 0x14000
	s_nop 0
	v_addc_co_u32_e32 v57, vcc, 0, v67, vcc
	global_load_ushort v155, v[56:57], off offset:2048
	v_add_co_u32_e32 v56, vcc, s0, v66
	s_mov_b32 s0, 0x17000
	s_nop 0
	v_addc_co_u32_e32 v57, vcc, 0, v67, vcc
	global_load_ushort v154, v[56:57], off offset:3072
	v_add_co_u32_e32 v56, vcc, s0, v66
	s_mov_b32 s0, 0x19000
	s_nop 0
	v_addc_co_u32_e32 v57, vcc, 0, v67, vcc
	global_load_ushort v153, v[56:57], off
	v_add_co_u32_e32 v56, vcc, s0, v66
	s_mov_b32 s0, 0x1b000
	s_nop 0
	v_addc_co_u32_e32 v57, vcc, 0, v67, vcc
	global_load_ushort v152, v[56:57], off offset:1024
	v_add_co_u32_e32 v56, vcc, s0, v66
	s_mov_b32 s0, 0x1d000
	s_nop 0
	v_addc_co_u32_e32 v57, vcc, 0, v67, vcc
	global_load_ushort v151, v[56:57], off offset:2048
	v_add_co_u32_e32 v56, vcc, s0, v66
	s_mov_b32 s0, 0x20000
	s_nop 0
	v_addc_co_u32_e32 v57, vcc, 0, v67, vcc
	global_load_ushort v112, v[56:57], off offset:3072
	v_add_co_u32_e32 v56, vcc, s0, v66
	s_mov_b32 s0, 0x22000
	s_nop 0
	v_addc_co_u32_e32 v57, vcc, 0, v67, vcc
	global_load_ushort v109, v[56:57], off
	v_add_co_u32_e32 v56, vcc, s0, v66
	v_add_u32_e32 v62, 0x9000, v149
	s_nop 0
	v_addc_co_u32_e32 v57, vcc, 0, v67, vcc
	global_load_ushort v107, v[56:57], off offset:1024
	ds_read2_b32 v[56:57], v62 offset1:68
	ds_read2_b32 v[58:59], v150 offset1:68
	s_lshl_b32 s0, s11, 6
	s_and_b32 s0, s0, 64
	s_andn2_b64 vcc, exec, s[4:5]
	s_waitcnt lgkmcnt(1)
	v_mul_f32_e32 v63, v56, v57
	s_waitcnt lgkmcnt(0)
	v_fma_f32 v58, 0, v56, v58
	v_fmac_f32_e32 v59, v58, v57
	ds_write2_b32 v150, v58, v59 offset1:68
	ds_read2_b32 v[56:57], v62 offset0:136 offset1:204
	ds_read2_b32 v[60:61], v150 offset0:136 offset1:204
	s_mov_b32 s1, s10
	s_waitcnt lgkmcnt(0)
	v_fma_f32 v58, v59, v56, v60
	v_mul_f32_e32 v56, v63, v56
	ds_write2_b32 v62, v63, v56 offset0:68 offset1:136
	v_fmac_f32_e32 v61, v58, v57
	v_add_u32_e32 v62, 0x9400, v149
	v_add_u32_e32 v63, 0x400, v150
	v_mul_f32_e32 v60, v56, v57
	ds_write2_b32 v150, v58, v61 offset0:136 offset1:204
	ds_read2_b32 v[56:57], v62 offset0:16 offset1:84
	ds_read2_b32 v[58:59], v63 offset0:16 offset1:84
	s_waitcnt lgkmcnt(0)
	v_fma_f32 v58, v61, v56, v58
	v_mul_f32_e32 v56, v60, v56
	v_add_u32_e32 v61, 0x9200, v149
	v_fmac_f32_e32 v59, v58, v57
	ds_write2_b32 v61, v60, v56 offset0:76 offset1:144
	ds_write2_b32 v63, v58, v59 offset0:16 offset1:84
	v_mul_f32_e32 v64, v56, v57
	ds_read2_b32 v[56:57], v62 offset0:152 offset1:220
	ds_read2_b32 v[60:61], v63 offset0:152 offset1:220
	s_waitcnt lgkmcnt(0)
	v_fma_f32 v58, v59, v56, v60
	v_mul_f32_e32 v56, v64, v56
	v_fmac_f32_e32 v61, v58, v57
	ds_write2_b32 v62, v64, v56 offset0:84 offset1:152
	ds_write2_b32 v63, v58, v61 offset0:152 offset1:220
	v_add_u32_e32 v62, 0x9800, v149
	v_add_u32_e32 v63, 0x800, v150
	v_mul_f32_e32 v60, v56, v57
	ds_read2_b32 v[56:57], v62 offset0:32 offset1:100
	ds_read2_b32 v[58:59], v63 offset0:32 offset1:100
	s_waitcnt lgkmcnt(0)
	v_fma_f32 v58, v61, v56, v58
	v_mul_f32_e32 v56, v60, v56
	v_add_u32_e32 v61, 0x9600, v149
	v_fmac_f32_e32 v59, v58, v57
	ds_write2_b32 v61, v60, v56 offset0:92 offset1:160
	ds_write2_b32 v63, v58, v59 offset0:32 offset1:100
	v_mul_f32_e32 v64, v56, v57
	ds_read2_b32 v[56:57], v62 offset0:168 offset1:236
	ds_read2_b32 v[60:61], v63 offset0:168 offset1:236
	s_waitcnt lgkmcnt(0)
	v_fma_f32 v58, v59, v56, v60
	v_mul_f32_e32 v56, v64, v56
	v_fmac_f32_e32 v61, v58, v57
	ds_write2_b32 v62, v64, v56 offset0:100 offset1:168
	ds_write2_b32 v63, v58, v61 offset0:168 offset1:236
	v_add_u32_e32 v62, 0x9c00, v149
	v_add_u32_e32 v63, 0xc00, v150
	v_mul_f32_e32 v60, v56, v57
	ds_read2_b32 v[56:57], v62 offset0:48 offset1:116
	ds_read2_b32 v[58:59], v63 offset0:48 offset1:116
	s_waitcnt lgkmcnt(0)
	v_fma_f32 v58, v61, v56, v58
	v_mul_f32_e32 v56, v60, v56
	v_add_u32_e32 v61, 0x9a00, v149
	v_fmac_f32_e32 v59, v58, v57
	ds_write2_b32 v61, v60, v56 offset0:108 offset1:176
	ds_write2_b32 v63, v58, v59 offset0:48 offset1:116
	v_mul_f32_e32 v60, v56, v57
	ds_read2_b32 v[56:57], v62 offset0:184 offset1:252
	ds_read2_b32 v[110:111], v63 offset0:184 offset1:252
	s_waitcnt lgkmcnt(0)
	v_fma_f32 v58, v59, v56, v110
	v_mul_f32_e32 v56, v60, v56
	v_fmac_f32_e32 v111, v58, v57
	ds_write2_b32 v62, v60, v56 offset0:116 offset1:184
	v_mul_f32_e32 v164, v56, v57
	ds_write2_b32 v63, v58, v111 offset0:184 offset1:252
	ds_write_b32 v149, v164 offset:40944
	ds_write_b32 v135, v164
	ds_write_b32 v136, v111
	s_waitcnt lgkmcnt(0)
	s_barrier
	ds_read_b32 v166, v150
	ds_read_b32 v182, v149 offset:36864
	ds_read_b32 v167, v150 offset:272
	ds_read_b32 v183, v149 offset:37136
	ds_read_b32 v168, v150 offset:544
	ds_read_b32 v184, v149 offset:37408
	ds_read_b32 v169, v150 offset:816
	ds_read_b32 v185, v149 offset:37680
	ds_read_b32 v170, v150 offset:1088
	ds_read_b32 v186, v149 offset:37952
	ds_read_b32 v171, v150 offset:1360
	ds_read_b32 v187, v149 offset:38224
	ds_read_b32 v172, v150 offset:1632
	ds_read_b32 v188, v149 offset:38496
	ds_read_b32 v173, v150 offset:1904
	ds_read_b32 v189, v149 offset:38768
	ds_read_b32 v174, v150 offset:2176
	ds_read_b32 v208, v149 offset:39040
	ds_read_b32 v175, v150 offset:2448
	ds_read_b32 v209, v149 offset:39312
	ds_read_b32 v176, v150 offset:2720
	ds_read_b32 v210, v149 offset:39584
	ds_read_b32 v177, v150 offset:2992
	ds_read_b32 v211, v149 offset:39856
	ds_read_b32 v178, v150 offset:3264
	ds_read_b32 v212, v149 offset:40128
	ds_read_b32 v179, v150 offset:3536
	ds_read_b32 v213, v149 offset:40400
	ds_read_b32 v180, v150 offset:3808
	ds_read_b32 v252, v149 offset:40672
	ds_read_b32 v181, v150 offset:4080
	ds_read_b32 v253, v149 offset:40944
	v_lshl_add_u32 v56, s0, 2, v129
	ds_read_b32 v110, v56
	v_mov_b32_e32 v56, v141
	s_cbranch_vccnz .LBB0_1096
